# v42: accumulator zeroing for the next GEMM unit moved into the P1 and P5 epilogues (interleaved with the stores), unit-head zero block skipped
# baseline (speedup 1.0000x reference)
.LBB0_364:
	s_add_u32 s12, s46, 0x7100000
	s_addc_u32 s13, s47, 0
	s_lshl_b32 s3, s3, 5
	s_mov_b64 s[14:15], 0x80
	s_and_b32 s3, s3, 0x60
	s_add_i32 m0, s9, 0x18000
	v_lshl_add_u64 v[8:9], v[8:9], 0, s[14:15]
	s_lshl_b32 s7, s2, 13
	s_lshl_b32 s17, s3, 7
	s_waitcnt vmcnt(2)
	s_barrier
	global_load_lds_dwordx4 v[8:9], off
	v_lshl_add_u64 v[6:7], v[6:7], 0, s[14:15]
	s_add_i32 m0, s9, 0x1a000
	s_add_i32 s40, s9, 0x8000
	s_add_i32 s41, s9, 0xa000
	global_load_lds_dwordx4 v[6:7], off
	v_lshl_add_u64 v[2:3], v[2:3], 0, s[14:15]
	s_mov_b32 m0, s40
	s_add_u32 s4, s28, 0x40080
	global_load_lds_dwordx4 v[2:3], off
	v_lshl_add_u64 v[2:3], v[4:5], 0, s[14:15]
	s_mov_b32 m0, s41
	s_addc_u32 s5, s29, 0
	global_load_lds_dwordx4 v[2:3], off
	s_add_i32 m0, s9, 0x1c000
	v_lshl_add_u64 v[2:3], s[4:5], 0, v[132:133]
	global_load_lds_dwordx4 v[2:3], off
	v_lshl_add_u64 v[2:3], s[4:5], 0, v[136:137]
	s_add_i32 m0, s9, 0x1e000
	v_lshlrev_b32_e32 v4, 2, v1
	global_load_lds_dwordx4 v[2:3], off
	v_and_b32_e32 v2, 15, v1
	v_lshlrev_b32_e32 v3, 1, v14
	v_lshl_or_b32 v141, s2, 6, v2
	v_lshl_or_b32 v2, v2, 6, v3
	v_and_b32_e32 v4, 32, v4
	v_bitop3_b32 v5, v2, s7, v4 bitop3:0xde
	v_lshlrev_b32_e32 v2, 6, v1
	s_movk_i32 s2, 0x3c0
	v_or_b32_e32 v140, s3, v14
	v_and_or_b32 v2, v2, s2, v3
	v_lshlrev_b32_e32 v138, 2, v140
	v_bitop3_b32 v156, s17, v2, v4 bitop3:0xf6
	v_lshl_add_u64 v[2:3], s[46:47], 0, v[138:139]
	s_mov_b64 s[4:5], 0x2000000
	v_lshl_add_u64 v[142:143], v[2:3], 0, s[4:5]
	v_lshlrev_b32_e32 v2, 8, v1
	v_and_b32_e32 v2, 0x38000, v2
	v_lshlrev_b32_e32 v3, 11, v12
	v_or3_b32 v2, v10, v2, v3
	v_add_u32_e32 v144, v2, v11
	v_lshlrev_b32_e32 v2, 4, v13
	s_waitcnt vmcnt(6)
	s_cmpk_lt_u32 s16, 0x100
	v_and_b32_e32 v2, 0x78000, v2
	s_cselect_b64 s[16:17], -1, 0
	v_or3_b32 v2, v10, v2, v3
	s_add_i32 s44, 0, 0x10000
	s_add_i32 s45, 0, 0x14000
	v_cmp_gt_u32_e64 s[2:3], 16, v140
	s_ashr_i32 s42, s91, 31
	s_ashr_i32 s43, s85, 31
	v_mov_b32_e32 v145, v139
	v_add_u32_e32 v146, v2, v11
	v_mov_b32_e32 v147, v139
	v_mov_b64_e32 v[148:149], 0x3fc
	v_mov_b64_e32 v[150:151], 0x3fb
	v_and_b32_e32 v158, 0x60, v140
	v_lshl_add_u32 v156, v158, 7, v156
	v_add_u32_e32 v157, s44, v156
	v_add_u32_e32 v158, 0x1000, v157
	v_add_u32_e32 v159, 0, v5
	s_movk_i32 s56, 0x1c00
	s_barrier
	s_mov_b32 s96, 0
	s_branch .LBB0_367

.LBB0_373:
	s_ashr_i32 s21, s20, 31
	s_lshl_b64 s[22:23], s[20:21], 19
	s_add_u32 s22, s33, s22
	s_addc_u32 s23, s34, s23
	s_and_b64 s[24:25], s[4:5], exec
	s_cselect_b32 s7, s23, s27
	s_cselect_b32 s21, s22, s26
	s_ashr_i32 s19, s18, 31
	s_lshl_b64 s[24:25], s[18:19], 19
	s_add_u32 s24, s46, s24
	s_addc_u32 s25, s47, s25
	s_and_b64 s[30:31], s[4:5], exec
	s_cselect_b32 s19, s25, s29
	s_cselect_b32 s57, s24, s28
	s_add_u32 s26, s26, 0x40080
	s_addc_u32 s27, s27, 0
	s_add_u32 s58, s28, 0x100
	v_mov_b32_e32 v2, 0
	s_addc_u32 s59, s29, 0
	s_mov_b32 s80, -2
	s_cmp_eq_u32 s96, 1
	s_cbranch_scc1 .Lp1_nozero
	v_mov_b32_e32 v3, v2
	v_mov_b32_e32 v4, v2
	v_mov_b32_e32 v5, v2
	v_mov_b32_e32 v6, v2
	v_mov_b32_e32 v7, v2
	v_mov_b32_e32 v8, v2
	v_mov_b32_e32 v9, v2
	v_mov_b32_e32 v18, v2
	v_mov_b32_e32 v19, v2
	v_mov_b32_e32 v20, v2
	v_mov_b32_e32 v21, v2
	v_mov_b32_e32 v22, v2
	v_mov_b32_e32 v23, v2
	v_mov_b32_e32 v24, v2
	v_mov_b32_e32 v25, v2
	v_mov_b32_e32 v34, v2
	v_mov_b32_e32 v35, v2
	v_mov_b32_e32 v36, v2
	v_mov_b32_e32 v37, v2
	v_mov_b32_e32 v38, v2
	v_mov_b32_e32 v39, v2
	v_mov_b32_e32 v40, v2
	v_mov_b32_e32 v41, v2
	v_mov_b32_e32 v50, v2
	v_mov_b32_e32 v51, v2
	v_mov_b32_e32 v52, v2
	v_mov_b32_e32 v53, v2
	v_mov_b32_e32 v54, v2
	v_mov_b32_e32 v55, v2
	v_mov_b32_e32 v56, v2
	v_mov_b32_e32 v57, v2
	v_mov_b32_e32 v10, v2
	v_mov_b32_e32 v11, v2
	v_mov_b32_e32 v12, v2
	v_mov_b32_e32 v13, v2
	v_mov_b32_e32 v14, v2
	v_mov_b32_e32 v15, v2
	v_mov_b32_e32 v16, v2
	v_mov_b32_e32 v17, v2
	v_mov_b32_e32 v26, v2
	v_mov_b32_e32 v27, v2
	v_mov_b32_e32 v28, v2
	v_mov_b32_e32 v29, v2
	v_mov_b32_e32 v30, v2
	v_mov_b32_e32 v31, v2
	v_mov_b32_e32 v32, v2
	v_mov_b32_e32 v33, v2
	v_mov_b32_e32 v42, v2
	v_mov_b32_e32 v43, v2
	v_mov_b32_e32 v44, v2
	v_mov_b32_e32 v45, v2
	v_mov_b32_e32 v46, v2
	v_mov_b32_e32 v47, v2
	v_mov_b32_e32 v48, v2
	v_mov_b32_e32 v49, v2
	v_mov_b32_e32 v58, v2
	v_mov_b32_e32 v59, v2
	v_mov_b32_e32 v60, v2
	v_mov_b32_e32 v61, v2
	v_mov_b32_e32 v62, v2
	v_mov_b32_e32 v63, v2
	v_mov_b32_e32 v64, v2
	v_mov_b32_e32 v65, v2
	v_mov_b32_e32 v66, v2
	v_mov_b32_e32 v67, v2
	v_mov_b32_e32 v68, v2
	v_mov_b32_e32 v69, v2
	v_mov_b32_e32 v70, v2
	v_mov_b32_e32 v71, v2
	v_mov_b32_e32 v72, v2
	v_mov_b32_e32 v73, v2
	v_mov_b32_e32 v82, v2
	v_mov_b32_e32 v83, v2
	v_mov_b32_e32 v84, v2
	v_mov_b32_e32 v85, v2
	v_mov_b32_e32 v86, v2
	v_mov_b32_e32 v87, v2
	v_mov_b32_e32 v88, v2
	v_mov_b32_e32 v89, v2
	v_mov_b32_e32 v98, v2
	v_mov_b32_e32 v99, v2
	v_mov_b32_e32 v100, v2
	v_mov_b32_e32 v101, v2
	v_mov_b32_e32 v102, v2
	v_mov_b32_e32 v103, v2
	v_mov_b32_e32 v104, v2
	v_mov_b32_e32 v105, v2
	v_mov_b32_e32 v114, v2
	v_mov_b32_e32 v115, v2
	v_mov_b32_e32 v116, v2
	v_mov_b32_e32 v117, v2
	v_mov_b32_e32 v118, v2
	v_mov_b32_e32 v119, v2
	v_mov_b32_e32 v120, v2
	v_mov_b32_e32 v121, v2
	v_mov_b32_e32 v74, v2
	v_mov_b32_e32 v75, v2
	v_mov_b32_e32 v76, v2
	v_mov_b32_e32 v77, v2
	v_mov_b32_e32 v78, v2
	v_mov_b32_e32 v79, v2
	v_mov_b32_e32 v80, v2
	v_mov_b32_e32 v81, v2
	v_mov_b32_e32 v90, v2
	v_mov_b32_e32 v91, v2
	v_mov_b32_e32 v92, v2
	v_mov_b32_e32 v93, v2
	v_mov_b32_e32 v94, v2
	v_mov_b32_e32 v95, v2
	v_mov_b32_e32 v96, v2
	v_mov_b32_e32 v97, v2
	v_mov_b32_e32 v106, v2
	v_mov_b32_e32 v107, v2
	v_mov_b32_e32 v108, v2
	v_mov_b32_e32 v109, v2
	v_mov_b32_e32 v110, v2
	v_mov_b32_e32 v111, v2
	v_mov_b32_e32 v112, v2
	v_mov_b32_e32 v113, v2
	v_mov_b32_e32 v122, v2
	v_mov_b32_e32 v123, v2
	v_mov_b32_e32 v124, v2
	v_mov_b32_e32 v125, v2
	v_mov_b32_e32 v126, v2
	v_mov_b32_e32 v127, v2
	v_mov_b32_e32 v128, v2
	v_mov_b32_e32 v129, v2
.Lp1_nozero:
.LBB0_374:
	ds_read_b128 v[152:155], v157
	ds_read_b128 v[160:163], v157 offset:1024
	ds_read_b128 v[164:167], v157 offset:2048
	ds_read_b128 v[168:171], v157 offset:3072
	ds_read_b128 v[172:175], v158
	ds_read_b128 v[176:179], v158 offset:1024
	ds_read_b128 v[180:183], v158 offset:2048
	ds_read_b128 v[184:187], v158 offset:3072
	s_add_u32 s28, s26, 0xfffc0080
	s_addc_u32 s29, s27, -1
	s_cmp_eq_u32 s80, 12
	s_cselect_b32 s31, s7, s29
	s_cselect_b32 s30, s21, s28
	s_cselect_b32 s29, s19, s59
	s_cselect_b32 s28, s57, s58
	v_lshl_add_u64 v[222:223], s[26:27], 0, v[144:145]
	s_add_i32 m0, s9, 0xc000
	ds_read_b128 v[188:191], v159
	ds_read_b128 v[192:195], v159 offset:1024
	ds_read_b128 v[196:199], v159 offset:2048
	ds_read_b128 v[200:203], v159 offset:3072
	ds_read_b128 v[204:207], v159 offset:4096
	ds_read_b128 v[210:213], v159 offset:5120
	ds_read_b128 v[214:217], v159 offset:6144
	ds_read_b128 v[218:221], v159 offset:7168
	global_load_lds_dwordx4 v[222:223], off
	v_lshl_add_u64 v[222:223], s[26:27], 0, v[146:147]
	s_add_i32 m0, s9, 0xe000
	s_nop 0
	global_load_lds_dwordx4 v[222:223], off
	s_waitcnt vmcnt(8)
	s_waitcnt lgkmcnt(0)
	s_barrier
	s_setprio 1
	s_waitcnt lgkmcnt(0)
	v_mfma_f32_16x16x32_bf16 v[126:129], v[152:155], v[188:191], v[126:129]
	v_mfma_f32_16x16x32_bf16 v[122:125], v[164:167], v[188:191], v[122:125]
	v_mfma_f32_16x16x32_bf16 v[110:113], v[152:155], v[196:199], v[110:113]
	v_mfma_f32_16x16x32_bf16 v[106:109], v[164:167], v[196:199], v[106:109]
	v_mfma_f32_16x16x32_bf16 v[94:97], v[152:155], v[204:207], v[94:97]
	v_mfma_f32_16x16x32_bf16 v[90:93], v[164:167], v[204:207], v[90:93]
	v_mfma_f32_16x16x32_bf16 v[78:81], v[152:155], v[214:217], v[78:81]
	v_mfma_f32_16x16x32_bf16 v[74:77], v[164:167], v[214:217], v[74:77]
	v_mfma_f32_16x16x32_bf16 v[126:129], v[160:163], v[192:195], v[126:129]
	v_mfma_f32_16x16x32_bf16 v[122:125], v[168:171], v[192:195], v[122:125]
	v_mfma_f32_16x16x32_bf16 v[110:113], v[160:163], v[200:203], v[110:113]
	v_mfma_f32_16x16x32_bf16 v[106:109], v[168:171], v[200:203], v[106:109]
	v_mfma_f32_16x16x32_bf16 v[94:97], v[160:163], v[210:213], v[94:97]
	v_mfma_f32_16x16x32_bf16 v[90:93], v[168:171], v[210:213], v[90:93]
	v_mfma_f32_16x16x32_bf16 v[78:81], v[160:163], v[218:221], v[78:81]
	v_mfma_f32_16x16x32_bf16 v[74:77], v[168:171], v[218:221], v[74:77]
	s_setprio 0
	s_setprio 1
	v_mfma_f32_16x16x32_bf16 v[118:121], v[172:175], v[188:191], v[118:121]
	v_mfma_f32_16x16x32_bf16 v[114:117], v[180:183], v[188:191], v[114:117]
	v_mfma_f32_16x16x32_bf16 v[102:105], v[172:175], v[196:199], v[102:105]
	v_mfma_f32_16x16x32_bf16 v[98:101], v[180:183], v[196:199], v[98:101]
	v_mfma_f32_16x16x32_bf16 v[86:89], v[172:175], v[204:207], v[86:89]
	v_mfma_f32_16x16x32_bf16 v[82:85], v[180:183], v[204:207], v[82:85]
	v_mfma_f32_16x16x32_bf16 v[70:73], v[172:175], v[214:217], v[70:73]
	v_mfma_f32_16x16x32_bf16 v[66:69], v[180:183], v[214:217], v[66:69]
	v_mfma_f32_16x16x32_bf16 v[118:121], v[176:179], v[192:195], v[118:121]
	v_mfma_f32_16x16x32_bf16 v[114:117], v[184:187], v[192:195], v[114:117]
	v_mfma_f32_16x16x32_bf16 v[102:105], v[176:179], v[200:203], v[102:105]
	v_mfma_f32_16x16x32_bf16 v[98:101], v[184:187], v[200:203], v[98:101]
	v_mfma_f32_16x16x32_bf16 v[86:89], v[176:179], v[210:213], v[86:89]
	v_mfma_f32_16x16x32_bf16 v[82:85], v[184:187], v[210:213], v[82:85]
	v_mfma_f32_16x16x32_bf16 v[70:73], v[176:179], v[218:221], v[70:73]
	v_mfma_f32_16x16x32_bf16 v[66:69], v[184:187], v[218:221], v[66:69]
	s_setprio 0
	s_barrier
	s_add_i32 s81, s44, s35
	v_lshl_add_u64 v[222:223], s[28:29], 0, v[132:133]
	s_mov_b32 m0, s81
	ds_read_b128 v[188:191], v159 offset:16384
	ds_read_b128 v[192:195], v159 offset:17408
	ds_read_b128 v[196:199], v159 offset:18432
	ds_read_b128 v[200:203], v159 offset:19456
	ds_read_b128 v[204:207], v159 offset:20480
	ds_read_b128 v[210:213], v159 offset:21504
	ds_read_b128 v[214:217], v159 offset:22528
	ds_read_b128 v[218:221], v159 offset:23552
	global_load_lds_dwordx4 v[222:223], off
	s_add_i32 m0, s81, 0x2000
	s_add_u32 s82, s28, 0x40000
	v_lshl_add_u64 v[224:225], s[28:29], 0, v[136:137]
	s_addc_u32 s83, s29, 0
	s_add_i32 s81, s45, s35
	global_load_lds_dwordx4 v[224:225], off
	v_lshl_add_u64 v[226:227], s[82:83], 0, v[132:133]
	s_mov_b32 m0, s81
	v_lshl_add_u64 v[228:229], s[30:31], 0, v[134:135]
	global_load_lds_dwordx4 v[226:227], off
	v_lshl_add_u64 v[226:227], s[82:83], 0, v[136:137]
	s_add_i32 m0, s81, 0x2000
	s_nop 0
	global_load_lds_dwordx4 v[226:227], off
	v_lshl_add_u64 v[226:227], s[30:31], 0, v[130:131]
	s_mov_b32 m0, s9
	s_nop 0
	global_load_lds_dwordx4 v[226:227], off
	s_mov_b32 m0, s36
	s_nop 0
	global_load_lds_dwordx4 v[228:229], off
	s_waitcnt vmcnt(8)
	s_waitcnt lgkmcnt(0)
	s_barrier
	s_setprio 1
	s_waitcnt lgkmcnt(0)
	v_mfma_f32_16x16x32_bf16 v[62:65], v[152:155], v[188:191], v[62:65]
	v_mfma_f32_16x16x32_bf16 v[58:61], v[164:167], v[188:191], v[58:61]
	v_mfma_f32_16x16x32_bf16 v[46:49], v[152:155], v[196:199], v[46:49]
	v_mfma_f32_16x16x32_bf16 v[42:45], v[164:167], v[196:199], v[42:45]
	v_mfma_f32_16x16x32_bf16 v[30:33], v[152:155], v[204:207], v[30:33]
	v_mfma_f32_16x16x32_bf16 v[26:29], v[164:167], v[204:207], v[26:29]
	v_mfma_f32_16x16x32_bf16 v[14:17], v[152:155], v[214:217], v[14:17]
	v_mfma_f32_16x16x32_bf16 v[10:13], v[164:167], v[214:217], v[10:13]
	v_mfma_f32_16x16x32_bf16 v[62:65], v[160:163], v[192:195], v[62:65]
	v_mfma_f32_16x16x32_bf16 v[58:61], v[168:171], v[192:195], v[58:61]
	v_mfma_f32_16x16x32_bf16 v[46:49], v[160:163], v[200:203], v[46:49]
	v_mfma_f32_16x16x32_bf16 v[42:45], v[168:171], v[200:203], v[42:45]
	v_mfma_f32_16x16x32_bf16 v[30:33], v[160:163], v[210:213], v[30:33]
	v_mfma_f32_16x16x32_bf16 v[26:29], v[168:171], v[210:213], v[26:29]
	v_mfma_f32_16x16x32_bf16 v[14:17], v[160:163], v[218:221], v[14:17]
	v_mfma_f32_16x16x32_bf16 v[10:13], v[168:171], v[218:221], v[10:13]
	s_setprio 0
	s_setprio 1
	v_mfma_f32_16x16x32_bf16 v[54:57], v[172:175], v[188:191], v[54:57]
	v_mfma_f32_16x16x32_bf16 v[50:53], v[180:183], v[188:191], v[50:53]
	v_mfma_f32_16x16x32_bf16 v[38:41], v[172:175], v[196:199], v[38:41]
	v_mfma_f32_16x16x32_bf16 v[34:37], v[180:183], v[196:199], v[34:37]
	v_mfma_f32_16x16x32_bf16 v[22:25], v[172:175], v[204:207], v[22:25]
	v_mfma_f32_16x16x32_bf16 v[18:21], v[180:183], v[204:207], v[18:21]
	v_mfma_f32_16x16x32_bf16 v[6:9], v[172:175], v[214:217], v[6:9]
	v_mfma_f32_16x16x32_bf16 v[2:5], v[180:183], v[214:217], v[2:5]
	v_mfma_f32_16x16x32_bf16 v[54:57], v[176:179], v[192:195], v[54:57]
	v_mfma_f32_16x16x32_bf16 v[50:53], v[184:187], v[192:195], v[50:53]
	v_mfma_f32_16x16x32_bf16 v[38:41], v[176:179], v[200:203], v[38:41]
	v_mfma_f32_16x16x32_bf16 v[34:37], v[184:187], v[200:203], v[34:37]
	v_mfma_f32_16x16x32_bf16 v[22:25], v[176:179], v[210:213], v[22:25]
	v_mfma_f32_16x16x32_bf16 v[18:21], v[184:187], v[210:213], v[18:21]
	v_mfma_f32_16x16x32_bf16 v[6:9], v[176:179], v[218:221], v[6:9]
	v_mfma_f32_16x16x32_bf16 v[2:5], v[184:187], v[218:221], v[2:5]
	s_setprio 0
	s_barrier
	s_add_i32 s81, 0, 0x18000
	v_add_u32_e32 v138, s81, v156
	s_add_i32 s82, 0, 0x1c000
	ds_read_b128 v[152:155], v138
	ds_read_b128 v[160:163], v138 offset:1024
	ds_read_b128 v[164:167], v138 offset:2048
	ds_read_b128 v[168:171], v138 offset:3072
	v_add_u32_e32 v138, 0x1000, v138
	ds_read_b128 v[172:175], v138
	ds_read_b128 v[176:179], v138 offset:1024
	ds_read_b128 v[180:183], v138 offset:2048
	ds_read_b128 v[184:187], v138 offset:3072
	s_add_u32 s30, s30, 0x40000
	s_addc_u32 s31, s31, 0
	s_mov_b32 m0, s37
	v_lshl_add_u64 v[230:231], s[30:31], 0, v[130:131]
	ds_read_b128 v[188:191], v159 offset:32768
	ds_read_b128 v[192:195], v159 offset:33792
	ds_read_b128 v[196:199], v159 offset:34816
	ds_read_b128 v[200:203], v159 offset:35840
	ds_read_b128 v[204:207], v159 offset:36864
	ds_read_b128 v[210:213], v159 offset:37888
	ds_read_b128 v[214:217], v159 offset:38912
	ds_read_b128 v[218:221], v159 offset:39936
	global_load_lds_dwordx4 v[230:231], off
	v_lshl_add_u64 v[230:231], s[30:31], 0, v[134:135]
	s_mov_b32 m0, s38
	s_nop 0
	global_load_lds_dwordx4 v[230:231], off
	s_waitcnt vmcnt(8)
	s_waitcnt lgkmcnt(0)
	s_barrier
	s_setprio 1
	s_waitcnt lgkmcnt(0)
	v_mfma_f32_16x16x32_bf16 v[126:129], v[152:155], v[188:191], v[126:129]
	v_mfma_f32_16x16x32_bf16 v[122:125], v[164:167], v[188:191], v[122:125]
	v_mfma_f32_16x16x32_bf16 v[110:113], v[152:155], v[196:199], v[110:113]
	v_mfma_f32_16x16x32_bf16 v[106:109], v[164:167], v[196:199], v[106:109]
	v_mfma_f32_16x16x32_bf16 v[94:97], v[152:155], v[204:207], v[94:97]
	v_mfma_f32_16x16x32_bf16 v[90:93], v[164:167], v[204:207], v[90:93]
	v_mfma_f32_16x16x32_bf16 v[78:81], v[152:155], v[214:217], v[78:81]
	v_mfma_f32_16x16x32_bf16 v[74:77], v[164:167], v[214:217], v[74:77]
	v_mfma_f32_16x16x32_bf16 v[126:129], v[160:163], v[192:195], v[126:129]
	v_mfma_f32_16x16x32_bf16 v[122:125], v[168:171], v[192:195], v[122:125]
	v_mfma_f32_16x16x32_bf16 v[110:113], v[160:163], v[200:203], v[110:113]
	v_mfma_f32_16x16x32_bf16 v[106:109], v[168:171], v[200:203], v[106:109]
	v_mfma_f32_16x16x32_bf16 v[94:97], v[160:163], v[210:213], v[94:97]
	v_mfma_f32_16x16x32_bf16 v[90:93], v[168:171], v[210:213], v[90:93]
	v_mfma_f32_16x16x32_bf16 v[78:81], v[160:163], v[218:221], v[78:81]
	v_mfma_f32_16x16x32_bf16 v[74:77], v[168:171], v[218:221], v[74:77]
	s_setprio 0
	s_setprio 1
	v_mfma_f32_16x16x32_bf16 v[118:121], v[172:175], v[188:191], v[118:121]
	v_mfma_f32_16x16x32_bf16 v[114:117], v[180:183], v[188:191], v[114:117]
	v_mfma_f32_16x16x32_bf16 v[102:105], v[172:175], v[196:199], v[102:105]
	v_mfma_f32_16x16x32_bf16 v[98:101], v[180:183], v[196:199], v[98:101]
	v_mfma_f32_16x16x32_bf16 v[86:89], v[172:175], v[204:207], v[86:89]
	v_mfma_f32_16x16x32_bf16 v[82:85], v[180:183], v[204:207], v[82:85]
	v_mfma_f32_16x16x32_bf16 v[70:73], v[172:175], v[214:217], v[70:73]
	v_mfma_f32_16x16x32_bf16 v[66:69], v[180:183], v[214:217], v[66:69]
	v_mfma_f32_16x16x32_bf16 v[118:121], v[176:179], v[192:195], v[118:121]
	v_mfma_f32_16x16x32_bf16 v[114:117], v[184:187], v[192:195], v[114:117]
	v_mfma_f32_16x16x32_bf16 v[102:105], v[176:179], v[200:203], v[102:105]
	v_mfma_f32_16x16x32_bf16 v[98:101], v[184:187], v[200:203], v[98:101]
	v_mfma_f32_16x16x32_bf16 v[86:89], v[176:179], v[210:213], v[86:89]
	v_mfma_f32_16x16x32_bf16 v[82:85], v[184:187], v[210:213], v[82:85]
	v_mfma_f32_16x16x32_bf16 v[70:73], v[176:179], v[218:221], v[70:73]
	v_mfma_f32_16x16x32_bf16 v[66:69], v[184:187], v[218:221], v[66:69]
	s_setprio 0
	s_barrier
	s_add_i32 s30, s81, s35
	v_lshl_add_u64 v[222:223], v[222:223], 0, s[14:15]
	s_mov_b32 m0, s30
	ds_read_b128 v[188:191], v159 offset:49152
	ds_read_b128 v[192:195], v159 offset:50176
	ds_read_b128 v[196:199], v159 offset:51200
	ds_read_b128 v[200:203], v159 offset:52224
	ds_read_b128 v[204:207], v159 offset:53248
	ds_read_b128 v[210:213], v159 offset:54272
	ds_read_b128 v[214:217], v159 offset:55296
	ds_read_b128 v[218:221], v159 offset:56320
	global_load_lds_dwordx4 v[222:223], off
	s_add_i32 m0, s30, 0x2000
	s_add_u32 s28, s28, 0x40080
	v_lshl_add_u64 v[222:223], v[224:225], 0, s[14:15]
	s_addc_u32 s29, s29, 0
	s_add_i32 s30, s82, s35
	global_load_lds_dwordx4 v[222:223], off
	v_lshl_add_u64 v[222:223], s[28:29], 0, v[132:133]
	s_mov_b32 m0, s30
	s_nop 0
	global_load_lds_dwordx4 v[222:223], off
	v_lshl_add_u64 v[222:223], s[28:29], 0, v[136:137]
	s_add_i32 m0, s30, 0x2000
	s_nop 0
	global_load_lds_dwordx4 v[222:223], off
	v_lshl_add_u64 v[222:223], v[226:227], 0, s[14:15]
	s_mov_b32 m0, s40
	s_nop 0
	global_load_lds_dwordx4 v[222:223], off
	v_lshl_add_u64 v[222:223], v[228:229], 0, s[14:15]
	s_mov_b32 m0, s41
	s_nop 0
	global_load_lds_dwordx4 v[222:223], off
	s_waitcnt vmcnt(8)
	s_waitcnt lgkmcnt(0)
	s_barrier
	s_setprio 1
	s_waitcnt lgkmcnt(0)
	v_mfma_f32_16x16x32_bf16 v[62:65], v[152:155], v[188:191], v[62:65]
	v_mfma_f32_16x16x32_bf16 v[58:61], v[164:167], v[188:191], v[58:61]
	v_mfma_f32_16x16x32_bf16 v[46:49], v[152:155], v[196:199], v[46:49]
	v_mfma_f32_16x16x32_bf16 v[42:45], v[164:167], v[196:199], v[42:45]
	v_mfma_f32_16x16x32_bf16 v[30:33], v[152:155], v[204:207], v[30:33]
	v_mfma_f32_16x16x32_bf16 v[26:29], v[164:167], v[204:207], v[26:29]
	v_mfma_f32_16x16x32_bf16 v[14:17], v[152:155], v[214:217], v[14:17]
	v_mfma_f32_16x16x32_bf16 v[10:13], v[164:167], v[214:217], v[10:13]
	v_mfma_f32_16x16x32_bf16 v[62:65], v[160:163], v[192:195], v[62:65]
	v_mfma_f32_16x16x32_bf16 v[58:61], v[168:171], v[192:195], v[58:61]
	v_mfma_f32_16x16x32_bf16 v[46:49], v[160:163], v[200:203], v[46:49]
	v_mfma_f32_16x16x32_bf16 v[42:45], v[168:171], v[200:203], v[42:45]
	v_mfma_f32_16x16x32_bf16 v[30:33], v[160:163], v[210:213], v[30:33]
	v_mfma_f32_16x16x32_bf16 v[26:29], v[168:171], v[210:213], v[26:29]
	v_mfma_f32_16x16x32_bf16 v[14:17], v[160:163], v[218:221], v[14:17]
	v_mfma_f32_16x16x32_bf16 v[10:13], v[168:171], v[218:221], v[10:13]
	s_setprio 0
	s_setprio 1
	v_mfma_f32_16x16x32_bf16 v[54:57], v[172:175], v[188:191], v[54:57]
	v_mfma_f32_16x16x32_bf16 v[50:53], v[180:183], v[188:191], v[50:53]
	v_mfma_f32_16x16x32_bf16 v[38:41], v[172:175], v[196:199], v[38:41]
	v_mfma_f32_16x16x32_bf16 v[34:37], v[180:183], v[196:199], v[34:37]
	v_mfma_f32_16x16x32_bf16 v[22:25], v[172:175], v[204:207], v[22:25]
	v_mfma_f32_16x16x32_bf16 v[18:21], v[180:183], v[204:207], v[18:21]
	v_mfma_f32_16x16x32_bf16 v[6:9], v[172:175], v[214:217], v[6:9]
	v_mfma_f32_16x16x32_bf16 v[2:5], v[180:183], v[214:217], v[2:5]
	v_mfma_f32_16x16x32_bf16 v[54:57], v[176:179], v[192:195], v[54:57]
	v_mfma_f32_16x16x32_bf16 v[50:53], v[184:187], v[192:195], v[50:53]
	v_mfma_f32_16x16x32_bf16 v[38:41], v[176:179], v[200:203], v[38:41]
	v_mfma_f32_16x16x32_bf16 v[34:37], v[184:187], v[200:203], v[34:37]
	v_mfma_f32_16x16x32_bf16 v[22:25], v[176:179], v[210:213], v[22:25]
	v_mfma_f32_16x16x32_bf16 v[18:21], v[184:187], v[210:213], v[18:21]
	v_mfma_f32_16x16x32_bf16 v[6:9], v[176:179], v[218:221], v[6:9]
	v_mfma_f32_16x16x32_bf16 v[2:5], v[184:187], v[218:221], v[2:5]
	s_setprio 0
	s_barrier
	s_add_i32 s80, s80, 2
	s_add_u32 s26, s26, 0x100
	s_addc_u32 s27, s27, 0
	s_add_u32 s58, s58, 0x100
	s_addc_u32 s59, s59, 0
	s_cmp_gt_u32 s80, 13
	s_cbranch_scc0 .LBB0_374
	s_and_b64 vcc, exec, s[16:17]
	s_cbranch_vccz .LBB0_377
	s_barrier
.LBB0_377:
	v_lshl_add_u32 v152, s6, 8, v141
	s_cmp_lg_u32 s8, 14
	s_cbranch_scc0 .Lp1e_lra
	v_and_b32_e32 v153, 8, v141
	v_sub_u32_e32 v160, v152, v153
	v_mul_u32_u24_e32 v160, 0x1c00, v160
	v_and_b32_e32 v161, 0x60, v140
	v_add_u32_e32 v161, v161, v140
	v_lshl_add_u32 v161, v153, 2, v161
	s_lshl_b32 s26, s8, 9
	v_lshl_add_u32 v161, v161, 1, s26
	v_add_u32_e32 v160, v160, v161
	s_mov_b32 s26, s12
	s_mov_b32 s27, s13
	v_cvt_pk_bf16_f32 v168, v118, v119
	v_cvt_pk_bf16_f32 v169, v120, v121
	v_cvt_pk_bf16_f32 v170, v114, v115
	v_cvt_pk_bf16_f32 v171, v116, v117
	v_cvt_pk_bf16_f32 v164, v126, v127
	v_cvt_pk_bf16_f32 v165, v128, v129
	v_cvt_pk_bf16_f32 v166, v122, v123
	v_cvt_pk_bf16_f32 v167, v124, v125
	v_mov_b32_e32 v172, v164
	v_mov_b32_e32 v173, v165
	v_mov_b32_e32 v174, v166
	v_mov_b32_e32 v175, v167
	v_mov_b32_dpp v172, v168 row_shr:8 row_mask:0xf bank_mask:0xc
	v_mov_b32_dpp v173, v169 row_shr:8 row_mask:0xf bank_mask:0xc
	v_mov_b32_dpp v174, v170 row_shr:8 row_mask:0xf bank_mask:0xc
	v_mov_b32_dpp v175, v171 row_shr:8 row_mask:0xf bank_mask:0xc
	v_mov_b32_dpp v168, v164 row_shl:8 row_mask:0xf bank_mask:0x3
	v_mov_b32_dpp v169, v165 row_shl:8 row_mask:0xf bank_mask:0x3
	v_mov_b32_dpp v170, v166 row_shl:8 row_mask:0xf bank_mask:0x3
	v_mov_b32_dpp v171, v167 row_shl:8 row_mask:0xf bank_mask:0x3
	global_store_dwordx4 v160, v[172:175], s[26:27]
	s_add_u32 s26, s26, 0xe000
	s_addc_u32 s27, s27, 0
	global_store_dwordx4 v160, v[168:171], s[26:27]
	s_add_u32 s26, s26, 0xe000
	s_addc_u32 s27, s27, 0
	v_mov_b32_e32 v114, 0
	v_mov_b32_e32 v115, 0
	v_mov_b32_e32 v116, 0
	v_mov_b32_e32 v117, 0
	v_mov_b32_e32 v118, 0
	v_mov_b32_e32 v119, 0
	v_mov_b32_e32 v120, 0
	v_mov_b32_e32 v121, 0
	v_mov_b32_e32 v122, 0
	v_mov_b32_e32 v123, 0
	v_mov_b32_e32 v124, 0
	v_mov_b32_e32 v125, 0
	v_mov_b32_e32 v126, 0
	v_mov_b32_e32 v127, 0
	v_mov_b32_e32 v128, 0
	v_mov_b32_e32 v129, 0
	v_cvt_pk_bf16_f32 v180, v102, v103
	v_cvt_pk_bf16_f32 v181, v104, v105
	v_cvt_pk_bf16_f32 v182, v98, v99
	v_cvt_pk_bf16_f32 v183, v100, v101
	v_cvt_pk_bf16_f32 v176, v110, v111
	v_cvt_pk_bf16_f32 v177, v112, v113
	v_cvt_pk_bf16_f32 v178, v106, v107
	v_cvt_pk_bf16_f32 v179, v108, v109
	v_mov_b32_e32 v184, v176
	v_mov_b32_e32 v185, v177
	v_mov_b32_e32 v186, v178
	v_mov_b32_e32 v187, v179
	v_mov_b32_dpp v184, v180 row_shr:8 row_mask:0xf bank_mask:0xc
	v_mov_b32_dpp v185, v181 row_shr:8 row_mask:0xf bank_mask:0xc
	v_mov_b32_dpp v186, v182 row_shr:8 row_mask:0xf bank_mask:0xc
	v_mov_b32_dpp v187, v183 row_shr:8 row_mask:0xf bank_mask:0xc
	v_mov_b32_dpp v180, v176 row_shl:8 row_mask:0xf bank_mask:0x3
	v_mov_b32_dpp v181, v177 row_shl:8 row_mask:0xf bank_mask:0x3
	v_mov_b32_dpp v182, v178 row_shl:8 row_mask:0xf bank_mask:0x3
	v_mov_b32_dpp v183, v179 row_shl:8 row_mask:0xf bank_mask:0x3
	global_store_dwordx4 v160, v[184:187], s[26:27]
	s_add_u32 s26, s26, 0xe000
	s_addc_u32 s27, s27, 0
	global_store_dwordx4 v160, v[180:183], s[26:27]
	s_add_u32 s26, s26, 0xe000
	s_addc_u32 s27, s27, 0
	v_mov_b32_e32 v98, 0
	v_mov_b32_e32 v99, 0
	v_mov_b32_e32 v100, 0
	v_mov_b32_e32 v101, 0
	v_mov_b32_e32 v102, 0
	v_mov_b32_e32 v103, 0
	v_mov_b32_e32 v104, 0
	v_mov_b32_e32 v105, 0
	v_mov_b32_e32 v106, 0
	v_mov_b32_e32 v107, 0
	v_mov_b32_e32 v108, 0
	v_mov_b32_e32 v109, 0
	v_mov_b32_e32 v110, 0
	v_mov_b32_e32 v111, 0
	v_mov_b32_e32 v112, 0
	v_mov_b32_e32 v113, 0
	v_cvt_pk_bf16_f32 v168, v86, v87
	v_cvt_pk_bf16_f32 v169, v88, v89
	v_cvt_pk_bf16_f32 v170, v82, v83
	v_cvt_pk_bf16_f32 v171, v84, v85
	v_cvt_pk_bf16_f32 v164, v94, v95
	v_cvt_pk_bf16_f32 v165, v96, v97
	v_cvt_pk_bf16_f32 v166, v90, v91
	v_cvt_pk_bf16_f32 v167, v92, v93
	v_mov_b32_e32 v172, v164
	v_mov_b32_e32 v173, v165
	v_mov_b32_e32 v174, v166
	v_mov_b32_e32 v175, v167
	v_mov_b32_dpp v172, v168 row_shr:8 row_mask:0xf bank_mask:0xc
	v_mov_b32_dpp v173, v169 row_shr:8 row_mask:0xf bank_mask:0xc
	v_mov_b32_dpp v174, v170 row_shr:8 row_mask:0xf bank_mask:0xc
	v_mov_b32_dpp v175, v171 row_shr:8 row_mask:0xf bank_mask:0xc
	v_mov_b32_dpp v168, v164 row_shl:8 row_mask:0xf bank_mask:0x3
	v_mov_b32_dpp v169, v165 row_shl:8 row_mask:0xf bank_mask:0x3
	v_mov_b32_dpp v170, v166 row_shl:8 row_mask:0xf bank_mask:0x3
	v_mov_b32_dpp v171, v167 row_shl:8 row_mask:0xf bank_mask:0x3
	global_store_dwordx4 v160, v[172:175], s[26:27]
	s_add_u32 s26, s26, 0xe000
	s_addc_u32 s27, s27, 0
	global_store_dwordx4 v160, v[168:171], s[26:27]
	s_add_u32 s26, s26, 0xe000
	s_addc_u32 s27, s27, 0
	v_mov_b32_e32 v82, 0
	v_mov_b32_e32 v83, 0
	v_mov_b32_e32 v84, 0
	v_mov_b32_e32 v85, 0
	v_mov_b32_e32 v86, 0
	v_mov_b32_e32 v87, 0
	v_mov_b32_e32 v88, 0
	v_mov_b32_e32 v89, 0
	v_mov_b32_e32 v90, 0
	v_mov_b32_e32 v91, 0
	v_mov_b32_e32 v92, 0
	v_mov_b32_e32 v93, 0
	v_mov_b32_e32 v94, 0
	v_mov_b32_e32 v95, 0
	v_mov_b32_e32 v96, 0
	v_mov_b32_e32 v97, 0
	v_cvt_pk_bf16_f32 v180, v70, v71
	v_cvt_pk_bf16_f32 v181, v72, v73
	v_cvt_pk_bf16_f32 v182, v66, v67
	v_cvt_pk_bf16_f32 v183, v68, v69
	v_cvt_pk_bf16_f32 v176, v78, v79
	v_cvt_pk_bf16_f32 v177, v80, v81
	v_cvt_pk_bf16_f32 v178, v74, v75
	v_cvt_pk_bf16_f32 v179, v76, v77
	v_mov_b32_e32 v184, v176
	v_mov_b32_e32 v185, v177
	v_mov_b32_e32 v186, v178
	v_mov_b32_e32 v187, v179
	v_mov_b32_dpp v184, v180 row_shr:8 row_mask:0xf bank_mask:0xc
	v_mov_b32_dpp v185, v181 row_shr:8 row_mask:0xf bank_mask:0xc
	v_mov_b32_dpp v186, v182 row_shr:8 row_mask:0xf bank_mask:0xc
	v_mov_b32_dpp v187, v183 row_shr:8 row_mask:0xf bank_mask:0xc
	v_mov_b32_dpp v180, v176 row_shl:8 row_mask:0xf bank_mask:0x3
	v_mov_b32_dpp v181, v177 row_shl:8 row_mask:0xf bank_mask:0x3
	v_mov_b32_dpp v182, v178 row_shl:8 row_mask:0xf bank_mask:0x3
	v_mov_b32_dpp v183, v179 row_shl:8 row_mask:0xf bank_mask:0x3
	global_store_dwordx4 v160, v[184:187], s[26:27]
	s_add_u32 s26, s26, 0xe000
	s_addc_u32 s27, s27, 0
	global_store_dwordx4 v160, v[180:183], s[26:27]
	s_add_u32 s26, s26, 0x7e000
	s_addc_u32 s27, s27, 0
	v_mov_b32_e32 v66, 0
	v_mov_b32_e32 v67, 0
	v_mov_b32_e32 v68, 0
	v_mov_b32_e32 v69, 0
	v_mov_b32_e32 v70, 0
	v_mov_b32_e32 v71, 0
	v_mov_b32_e32 v72, 0
	v_mov_b32_e32 v73, 0
	v_mov_b32_e32 v74, 0
	v_mov_b32_e32 v75, 0
	v_mov_b32_e32 v76, 0
	v_mov_b32_e32 v77, 0
	v_mov_b32_e32 v78, 0
	v_mov_b32_e32 v79, 0
	v_mov_b32_e32 v80, 0
	v_mov_b32_e32 v81, 0
	v_cvt_pk_bf16_f32 v168, v54, v55
	v_cvt_pk_bf16_f32 v169, v56, v57
	v_cvt_pk_bf16_f32 v170, v50, v51
	v_cvt_pk_bf16_f32 v171, v52, v53
	v_cvt_pk_bf16_f32 v164, v62, v63
	v_cvt_pk_bf16_f32 v165, v64, v65
	v_cvt_pk_bf16_f32 v166, v58, v59
	v_cvt_pk_bf16_f32 v167, v60, v61
	v_mov_b32_e32 v172, v164
	v_mov_b32_e32 v173, v165
	v_mov_b32_e32 v174, v166
	v_mov_b32_e32 v175, v167
	v_mov_b32_dpp v172, v168 row_shr:8 row_mask:0xf bank_mask:0xc
	v_mov_b32_dpp v173, v169 row_shr:8 row_mask:0xf bank_mask:0xc
	v_mov_b32_dpp v174, v170 row_shr:8 row_mask:0xf bank_mask:0xc
	v_mov_b32_dpp v175, v171 row_shr:8 row_mask:0xf bank_mask:0xc
	v_mov_b32_dpp v168, v164 row_shl:8 row_mask:0xf bank_mask:0x3
	v_mov_b32_dpp v169, v165 row_shl:8 row_mask:0xf bank_mask:0x3
	v_mov_b32_dpp v170, v166 row_shl:8 row_mask:0xf bank_mask:0x3
	v_mov_b32_dpp v171, v167 row_shl:8 row_mask:0xf bank_mask:0x3
	global_store_dwordx4 v160, v[172:175], s[26:27]
	s_add_u32 s26, s26, 0xe000
	s_addc_u32 s27, s27, 0
	global_store_dwordx4 v160, v[168:171], s[26:27]
	s_add_u32 s26, s26, 0xe000
	s_addc_u32 s27, s27, 0
	v_mov_b32_e32 v50, 0
	v_mov_b32_e32 v51, 0
	v_mov_b32_e32 v52, 0
	v_mov_b32_e32 v53, 0
	v_mov_b32_e32 v54, 0
	v_mov_b32_e32 v55, 0
	v_mov_b32_e32 v56, 0
	v_mov_b32_e32 v57, 0
	v_mov_b32_e32 v58, 0
	v_mov_b32_e32 v59, 0
	v_mov_b32_e32 v60, 0
	v_mov_b32_e32 v61, 0
	v_mov_b32_e32 v62, 0
	v_mov_b32_e32 v63, 0
	v_mov_b32_e32 v64, 0
	v_mov_b32_e32 v65, 0
	v_cvt_pk_bf16_f32 v180, v38, v39
	v_cvt_pk_bf16_f32 v181, v40, v41
	v_cvt_pk_bf16_f32 v182, v34, v35
	v_cvt_pk_bf16_f32 v183, v36, v37
	v_cvt_pk_bf16_f32 v176, v46, v47
	v_cvt_pk_bf16_f32 v177, v48, v49
	v_cvt_pk_bf16_f32 v178, v42, v43
	v_cvt_pk_bf16_f32 v179, v44, v45
	v_mov_b32_e32 v184, v176
	v_mov_b32_e32 v185, v177
	v_mov_b32_e32 v186, v178
	v_mov_b32_e32 v187, v179
	v_mov_b32_dpp v184, v180 row_shr:8 row_mask:0xf bank_mask:0xc
	v_mov_b32_dpp v185, v181 row_shr:8 row_mask:0xf bank_mask:0xc
	v_mov_b32_dpp v186, v182 row_shr:8 row_mask:0xf bank_mask:0xc
	v_mov_b32_dpp v187, v183 row_shr:8 row_mask:0xf bank_mask:0xc
	v_mov_b32_dpp v180, v176 row_shl:8 row_mask:0xf bank_mask:0x3
	v_mov_b32_dpp v181, v177 row_shl:8 row_mask:0xf bank_mask:0x3
	v_mov_b32_dpp v182, v178 row_shl:8 row_mask:0xf bank_mask:0x3
	v_mov_b32_dpp v183, v179 row_shl:8 row_mask:0xf bank_mask:0x3
	global_store_dwordx4 v160, v[184:187], s[26:27]
	s_add_u32 s26, s26, 0xe000
	s_addc_u32 s27, s27, 0
	global_store_dwordx4 v160, v[180:183], s[26:27]
	s_add_u32 s26, s26, 0xe000
	s_addc_u32 s27, s27, 0
	v_mov_b32_e32 v34, 0
	v_mov_b32_e32 v35, 0
	v_mov_b32_e32 v36, 0
	v_mov_b32_e32 v37, 0
	v_mov_b32_e32 v38, 0
	v_mov_b32_e32 v39, 0
	v_mov_b32_e32 v40, 0
	v_mov_b32_e32 v41, 0
	v_mov_b32_e32 v42, 0
	v_mov_b32_e32 v43, 0
	v_mov_b32_e32 v44, 0
	v_mov_b32_e32 v45, 0
	v_mov_b32_e32 v46, 0
	v_mov_b32_e32 v47, 0
	v_mov_b32_e32 v48, 0
	v_mov_b32_e32 v49, 0
	v_cvt_pk_bf16_f32 v168, v22, v23
	v_cvt_pk_bf16_f32 v169, v24, v25
	v_cvt_pk_bf16_f32 v170, v18, v19
	v_cvt_pk_bf16_f32 v171, v20, v21
	v_cvt_pk_bf16_f32 v164, v30, v31
	v_cvt_pk_bf16_f32 v165, v32, v33
	v_cvt_pk_bf16_f32 v166, v26, v27
	v_cvt_pk_bf16_f32 v167, v28, v29
	v_mov_b32_e32 v172, v164
	v_mov_b32_e32 v173, v165
	v_mov_b32_e32 v174, v166
	v_mov_b32_e32 v175, v167
	v_mov_b32_dpp v172, v168 row_shr:8 row_mask:0xf bank_mask:0xc
	v_mov_b32_dpp v173, v169 row_shr:8 row_mask:0xf bank_mask:0xc
	v_mov_b32_dpp v174, v170 row_shr:8 row_mask:0xf bank_mask:0xc
	v_mov_b32_dpp v175, v171 row_shr:8 row_mask:0xf bank_mask:0xc
	v_mov_b32_dpp v168, v164 row_shl:8 row_mask:0xf bank_mask:0x3
	v_mov_b32_dpp v169, v165 row_shl:8 row_mask:0xf bank_mask:0x3
	v_mov_b32_dpp v170, v166 row_shl:8 row_mask:0xf bank_mask:0x3
	v_mov_b32_dpp v171, v167 row_shl:8 row_mask:0xf bank_mask:0x3
	global_store_dwordx4 v160, v[172:175], s[26:27]
	s_add_u32 s26, s26, 0xe000
	s_addc_u32 s27, s27, 0
	global_store_dwordx4 v160, v[168:171], s[26:27]
	s_add_u32 s26, s26, 0xe000
	s_addc_u32 s27, s27, 0
	v_mov_b32_e32 v18, 0
	v_mov_b32_e32 v19, 0
	v_mov_b32_e32 v20, 0
	v_mov_b32_e32 v21, 0
	v_mov_b32_e32 v22, 0
	v_mov_b32_e32 v23, 0
	v_mov_b32_e32 v24, 0
	v_mov_b32_e32 v25, 0
	v_mov_b32_e32 v26, 0
	v_mov_b32_e32 v27, 0
	v_mov_b32_e32 v28, 0
	v_mov_b32_e32 v29, 0
	v_mov_b32_e32 v30, 0
	v_mov_b32_e32 v31, 0
	v_mov_b32_e32 v32, 0
	v_mov_b32_e32 v33, 0
	v_cvt_pk_bf16_f32 v180, v6, v7
	v_cvt_pk_bf16_f32 v181, v8, v9
	v_cvt_pk_bf16_f32 v182, v2, v3
	v_cvt_pk_bf16_f32 v183, v4, v5
	v_cvt_pk_bf16_f32 v176, v14, v15
	v_cvt_pk_bf16_f32 v177, v16, v17
	v_cvt_pk_bf16_f32 v178, v10, v11
	v_cvt_pk_bf16_f32 v179, v12, v13
	v_mov_b32_e32 v184, v176
	v_mov_b32_e32 v185, v177
	v_mov_b32_e32 v186, v178
	v_mov_b32_e32 v187, v179
	v_mov_b32_dpp v184, v180 row_shr:8 row_mask:0xf bank_mask:0xc
	v_mov_b32_dpp v185, v181 row_shr:8 row_mask:0xf bank_mask:0xc
	v_mov_b32_dpp v186, v182 row_shr:8 row_mask:0xf bank_mask:0xc
	v_mov_b32_dpp v187, v183 row_shr:8 row_mask:0xf bank_mask:0xc
	v_mov_b32_dpp v180, v176 row_shl:8 row_mask:0xf bank_mask:0x3
	v_mov_b32_dpp v181, v177 row_shl:8 row_mask:0xf bank_mask:0x3
	v_mov_b32_dpp v182, v178 row_shl:8 row_mask:0xf bank_mask:0x3
	v_mov_b32_dpp v183, v179 row_shl:8 row_mask:0xf bank_mask:0x3
	global_store_dwordx4 v160, v[184:187], s[26:27]
	s_add_u32 s26, s26, 0xe000
	s_addc_u32 s27, s27, 0
	global_store_dwordx4 v160, v[180:183], s[26:27]
	v_mov_b32_e32 v2, 0
	v_mov_b32_e32 v3, 0
	v_mov_b32_e32 v4, 0
	v_mov_b32_e32 v5, 0
	v_mov_b32_e32 v6, 0
	v_mov_b32_e32 v7, 0
	v_mov_b32_e32 v8, 0
	v_mov_b32_e32 v9, 0
	v_mov_b32_e32 v10, 0
	v_mov_b32_e32 v11, 0
	v_mov_b32_e32 v12, 0
	v_mov_b32_e32 v13, 0
	v_mov_b32_e32 v14, 0
	v_mov_b32_e32 v15, 0
	v_mov_b32_e32 v16, 0
	v_mov_b32_e32 v17, 0
	s_mov_b32 s96, 1
	s_branch .LBB0_441
.Lp1e_lra:
	s_mov_b32 s96, 0
	s_and_saveexec_b64 s[26:27], s[2:3]
	s_cbranch_execz .Lp1e_lra_done
	v_ashrrev_i32_e32 v153, 31, v152
	v_lshlrev_b64 v[160:161], 6, v[152:153]
	v_lshl_add_u64 v[160:161], v[142:143], 0, v[160:161]
	global_store_dwordx4 v[160:161], v[126:129], off
	global_store_dwordx4 v[160:161], v[122:125], off offset:16
	global_store_dwordx4 v[160:161], v[110:113], off offset:1024
	global_store_dwordx4 v[160:161], v[106:109], off offset:1040
	global_store_dwordx4 v[160:161], v[94:97], off offset:2048
	global_store_dwordx4 v[160:161], v[90:93], off offset:2064
	global_store_dwordx4 v[160:161], v[78:81], off offset:3072
	global_store_dwordx4 v[160:161], v[74:77], off offset:3088
	v_add_co_u32_e32 v160, vcc, 0x2000, v160
	s_nop 1
	v_addc_co_u32_e32 v161, vcc, 0, v161, vcc
	global_store_dwordx4 v[160:161], v[62:65], off
	global_store_dwordx4 v[160:161], v[58:61], off offset:16
	global_store_dwordx4 v[160:161], v[46:49], off offset:1024
	global_store_dwordx4 v[160:161], v[42:45], off offset:1040
	global_store_dwordx4 v[160:161], v[30:33], off offset:2048
	global_store_dwordx4 v[160:161], v[26:29], off offset:2064
	global_store_dwordx4 v[160:161], v[14:17], off offset:3072
	global_store_dwordx4 v[160:161], v[10:13], off offset:3088
